# q/k epilogue: output scale folded into the norm-gain registers once per block (128 fewer f32 multiplies per wave per q/k tile)
# speedup vs baseline: 1.0041x; 1.0041x over previous
.Lq0_rows:
	ds_read_b128 v[200:203], v192
	ds_read_b128 v[204:207], v192 offset:16
	v_mul_u32_u24_e32 v246, s33, v146
	v_add3_u32 v246, v246, v138, v136
	s_lshl_b32 s0, s10, 1
	v_add_u32_e32 v246, s0, v246
	v_mov_b32_e32 v209, s93
	v_add_co_u32_e32 v208, vcc, s92, v246
	s_nop 1
	v_addc_co_u32_e32 v209, vcc, 0, v209, vcc
	s_mov_b32 vcc_lo, 0x12000
	s_mov_b32 vcc_hi, 0
	s_mov_b32 s26, 0x3c800000
	s_waitcnt lgkmcnt(0)
	v_mul_f32_e32 v184, s28, v184
	v_mul_f32_e32 v185, s28, v185
	v_mul_f32_e32 v186, s28, v186
	v_mul_f32_e32 v187, s28, v187
	v_mul_f32_e32 v188, s28, v188
	v_mul_f32_e32 v189, s28, v189
	v_mul_f32_e32 v190, s28, v190
	v_mul_f32_e32 v191, s28, v191
	ds_read_b128 v[214:217], v193
	ds_read_b128 v[218:221], v193 offset:16
	v_add_f32_e32 v246, v238, v222
	v_fma_f32 v246, v246, s26, v230
	v_rsq_f32_e32 v246, v246
	v_lshl_add_u64 v[248:249], vcc, 0, v[208:209]
	v_mul_f32_e32 v120, v120, v246
	v_mul_f32_e32 v121, v121, v246
	v_mul_f32_e32 v122, v122, v246
	v_mul_f32_e32 v123, v123, v246
	v_mul_f32_e32 v124, v124, v246
	v_mul_f32_e32 v125, v125, v246
	v_mul_f32_e32 v126, v126, v246
	v_mul_f32_e32 v127, v127, v246
	v_mul_f32_e32 v120, v184, v120
	v_mul_f32_e32 v121, v185, v121
	v_mul_f32_e32 v122, v186, v122
	v_mul_f32_e32 v123, v187, v123
	v_mul_f32_e32 v124, v188, v124
	v_mul_f32_e32 v125, v189, v125
	v_mul_f32_e32 v126, v190, v126
	v_mul_f32_e32 v127, v191, v127
	v_mul_f32_e32 v246, v201, v124
	v_mul_f32_e32 v247, v200, v124
	v_fma_f32 v124, v201, v120, v247
	v_fma_f32 v120, v200, v120, -v246
	v_mul_f32_e32 v246, v203, v125
	v_mul_f32_e32 v247, v202, v125
	v_fma_f32 v125, v203, v121, v247
	v_fma_f32 v121, v202, v121, -v246
	v_mul_f32_e32 v246, v205, v126
	v_mul_f32_e32 v247, v204, v126
	v_fma_f32 v126, v205, v122, v247
	v_fma_f32 v122, v204, v122, -v246
	v_mul_f32_e32 v246, v207, v127
	v_mul_f32_e32 v247, v206, v127
	v_fma_f32 v127, v207, v123, v247
	v_fma_f32 v123, v206, v123, -v246
	v_cvt_pk_bf16_f32 v232, v120, v121
	v_cvt_pk_bf16_f32 v233, v122, v123
	v_cvt_pk_bf16_f32 v234, v124, v125
	v_cvt_pk_bf16_f32 v235, v126, v127
	s_nop 1
	v_permlane16_swap_b32_e32 v232, v234
	v_permlane16_swap_b32_e32 v233, v235
	global_store_dwordx4 v[208:209], v[232:235], off
	s_waitcnt lgkmcnt(0)
	ds_read_b128 v[200:203], v194
	ds_read_b128 v[204:207], v194 offset:16
	v_add_f32_e32 v246, v239, v223
	v_fma_f32 v246, v246, s26, v230
	v_rsq_f32_e32 v246, v246
	v_lshl_add_u64 v[208:209], vcc, 0, v[248:249]
	v_mul_f32_e32 v112, v112, v246
	v_mul_f32_e32 v113, v113, v246
	v_mul_f32_e32 v114, v114, v246
	v_mul_f32_e32 v115, v115, v246
	v_mul_f32_e32 v116, v116, v246
	v_mul_f32_e32 v117, v117, v246
	v_mul_f32_e32 v118, v118, v246
	v_mul_f32_e32 v119, v119, v246
	v_mul_f32_e32 v112, v184, v112
	v_mul_f32_e32 v113, v185, v113
	v_mul_f32_e32 v114, v186, v114
	v_mul_f32_e32 v115, v187, v115
	v_mul_f32_e32 v116, v188, v116
	v_mul_f32_e32 v117, v189, v117
	v_mul_f32_e32 v118, v190, v118
	v_mul_f32_e32 v119, v191, v119
	v_mul_f32_e32 v246, v215, v116
	v_mul_f32_e32 v247, v214, v116
	v_fma_f32 v116, v215, v112, v247
	v_fma_f32 v112, v214, v112, -v246
	v_mul_f32_e32 v246, v217, v117
	v_mul_f32_e32 v247, v216, v117
	v_fma_f32 v117, v217, v113, v247
	v_fma_f32 v113, v216, v113, -v246
	v_mul_f32_e32 v246, v219, v118
	v_mul_f32_e32 v247, v218, v118
	v_fma_f32 v118, v219, v114, v247
	v_fma_f32 v114, v218, v114, -v246
	v_mul_f32_e32 v246, v221, v119
	v_mul_f32_e32 v247, v220, v119
	v_fma_f32 v119, v221, v115, v247
	v_fma_f32 v115, v220, v115, -v246
	v_cvt_pk_bf16_f32 v32, v112, v113
	v_cvt_pk_bf16_f32 v33, v114, v115
	v_cvt_pk_bf16_f32 v34, v116, v117
	v_cvt_pk_bf16_f32 v35, v118, v119
	s_nop 1
	v_permlane16_swap_b32_e32 v32, v34
	v_permlane16_swap_b32_e32 v33, v35
	global_store_dwordx4 v[248:249], v[32:35], off
	s_waitcnt lgkmcnt(0)
	ds_read_b128 v[214:217], v195
	ds_read_b128 v[218:221], v195 offset:16
	v_add_f32_e32 v246, v240, v224
	v_fma_f32 v246, v246, s26, v230
	v_rsq_f32_e32 v246, v246
	v_lshl_add_u64 v[248:249], vcc, 0, v[208:209]
	v_mul_f32_e32 v104, v104, v246
	v_mul_f32_e32 v105, v105, v246
	v_mul_f32_e32 v106, v106, v246
	v_mul_f32_e32 v107, v107, v246
	v_mul_f32_e32 v108, v108, v246
	v_mul_f32_e32 v109, v109, v246
	v_mul_f32_e32 v110, v110, v246
	v_mul_f32_e32 v111, v111, v246
	v_mul_f32_e32 v104, v184, v104
	v_mul_f32_e32 v105, v185, v105
	v_mul_f32_e32 v106, v186, v106
	v_mul_f32_e32 v107, v187, v107
	v_mul_f32_e32 v108, v188, v108
	v_mul_f32_e32 v109, v189, v109
	v_mul_f32_e32 v110, v190, v110
	v_mul_f32_e32 v111, v191, v111
	v_mul_f32_e32 v246, v201, v108
	v_mul_f32_e32 v247, v200, v108
	v_fma_f32 v108, v201, v104, v247
	v_fma_f32 v104, v200, v104, -v246
	v_mul_f32_e32 v246, v203, v109
	v_mul_f32_e32 v247, v202, v109
	v_fma_f32 v109, v203, v105, v247
	v_fma_f32 v105, v202, v105, -v246
	v_mul_f32_e32 v246, v205, v110
	v_mul_f32_e32 v247, v204, v110
	v_fma_f32 v110, v205, v106, v247
	v_fma_f32 v106, v204, v106, -v246
	v_mul_f32_e32 v246, v207, v111
	v_mul_f32_e32 v247, v206, v111
	v_fma_f32 v111, v207, v107, v247
	v_fma_f32 v107, v206, v107, -v246
	v_cvt_pk_bf16_f32 v232, v104, v105
	v_cvt_pk_bf16_f32 v233, v106, v107
	v_cvt_pk_bf16_f32 v234, v108, v109
	v_cvt_pk_bf16_f32 v235, v110, v111
	s_nop 1
	v_permlane16_swap_b32_e32 v232, v234
	v_permlane16_swap_b32_e32 v233, v235
	global_store_dwordx4 v[208:209], v[232:235], off
	s_waitcnt lgkmcnt(0)
	ds_read_b128 v[200:203], v196
	ds_read_b128 v[204:207], v196 offset:16
	v_add_f32_e32 v246, v241, v225
	v_fma_f32 v246, v246, s26, v230
	v_rsq_f32_e32 v246, v246
	s_mov_b32 vcc_lo, 0x5a000
	v_lshl_add_u64 v[208:209], vcc, 0, v[248:249]
	s_mov_b32 vcc_lo, 0x12000
	v_mul_f32_e32 v96, v96, v246
	v_mul_f32_e32 v97, v97, v246
	v_mul_f32_e32 v98, v98, v246
	v_mul_f32_e32 v99, v99, v246
	v_mul_f32_e32 v100, v100, v246
	v_mul_f32_e32 v101, v101, v246
	v_mul_f32_e32 v102, v102, v246
	v_mul_f32_e32 v103, v103, v246
	v_mul_f32_e32 v96, v184, v96
	v_mul_f32_e32 v97, v185, v97
	v_mul_f32_e32 v98, v186, v98
	v_mul_f32_e32 v99, v187, v99
	v_mul_f32_e32 v100, v188, v100
	v_mul_f32_e32 v101, v189, v101
	v_mul_f32_e32 v102, v190, v102
	v_mul_f32_e32 v103, v191, v103
	v_mul_f32_e32 v246, v215, v100
	v_mul_f32_e32 v247, v214, v100
	v_fma_f32 v100, v215, v96, v247
	v_fma_f32 v96, v214, v96, -v246
	v_mul_f32_e32 v246, v217, v101
	v_mul_f32_e32 v247, v216, v101
	v_fma_f32 v101, v217, v97, v247
	v_fma_f32 v97, v216, v97, -v246
	v_mul_f32_e32 v246, v219, v102
	v_mul_f32_e32 v247, v218, v102
	v_fma_f32 v102, v219, v98, v247
	v_fma_f32 v98, v218, v98, -v246
	v_mul_f32_e32 v246, v221, v103
	v_mul_f32_e32 v247, v220, v103
	v_fma_f32 v103, v221, v99, v247
	v_fma_f32 v99, v220, v99, -v246
	v_cvt_pk_bf16_f32 v32, v96, v97
	v_cvt_pk_bf16_f32 v33, v98, v99
	v_cvt_pk_bf16_f32 v34, v100, v101
	v_cvt_pk_bf16_f32 v35, v102, v103
	s_nop 1
	v_permlane16_swap_b32_e32 v32, v34
	v_permlane16_swap_b32_e32 v33, v35
	global_store_dwordx4 v[248:249], v[32:35], off
	s_waitcnt lgkmcnt(0)
	ds_read_b128 v[214:217], v197
	ds_read_b128 v[218:221], v197 offset:16
	v_add_f32_e32 v246, v242, v226
	v_fma_f32 v246, v246, s26, v230
	v_rsq_f32_e32 v246, v246
	v_lshl_add_u64 v[248:249], vcc, 0, v[208:209]
	v_mul_f32_e32 v88, v88, v246
	v_mul_f32_e32 v89, v89, v246
	v_mul_f32_e32 v90, v90, v246
	v_mul_f32_e32 v91, v91, v246
	v_mul_f32_e32 v210, v210, v246
	v_mul_f32_e32 v211, v211, v246
	v_mul_f32_e32 v212, v212, v246
	v_mul_f32_e32 v213, v213, v246
	v_mul_f32_e32 v88, v184, v88
	v_mul_f32_e32 v89, v185, v89
	v_mul_f32_e32 v90, v186, v90
	v_mul_f32_e32 v91, v187, v91
	v_mul_f32_e32 v210, v188, v210
	v_mul_f32_e32 v211, v189, v211
	v_mul_f32_e32 v212, v190, v212
	v_mul_f32_e32 v213, v191, v213
	v_mul_f32_e32 v246, v201, v210
	v_mul_f32_e32 v247, v200, v210
	v_fma_f32 v210, v201, v88, v247
	v_fma_f32 v88, v200, v88, -v246
	v_mul_f32_e32 v246, v203, v211
	v_mul_f32_e32 v247, v202, v211
	v_fma_f32 v211, v203, v89, v247
	v_fma_f32 v89, v202, v89, -v246
	v_mul_f32_e32 v246, v205, v212
	v_mul_f32_e32 v247, v204, v212
	v_fma_f32 v212, v205, v90, v247
	v_fma_f32 v90, v204, v90, -v246
	v_mul_f32_e32 v246, v207, v213
	v_mul_f32_e32 v247, v206, v213
	v_fma_f32 v213, v207, v91, v247
	v_fma_f32 v91, v206, v91, -v246
	v_cvt_pk_bf16_f32 v232, v88, v89
	v_cvt_pk_bf16_f32 v233, v90, v91
	v_cvt_pk_bf16_f32 v234, v210, v211
	v_cvt_pk_bf16_f32 v235, v212, v213
	s_nop 1
	v_permlane16_swap_b32_e32 v232, v234
	v_permlane16_swap_b32_e32 v233, v235
	global_store_dwordx4 v[208:209], v[232:235], off
	s_waitcnt lgkmcnt(0)
	ds_read_b128 v[200:203], v198
	ds_read_b128 v[204:207], v198 offset:16
	v_add_f32_e32 v246, v243, v227
	v_fma_f32 v246, v246, s26, v230
	v_rsq_f32_e32 v246, v246
	v_lshl_add_u64 v[208:209], vcc, 0, v[248:249]
	v_mul_f32_e32 v80, v80, v246
	v_mul_f32_e32 v81, v81, v246
	v_mul_f32_e32 v82, v82, v246
	v_mul_f32_e32 v83, v83, v246
	v_mul_f32_e32 v84, v84, v246
	v_mul_f32_e32 v85, v85, v246
	v_mul_f32_e32 v86, v86, v246
	v_mul_f32_e32 v87, v87, v246
	v_mul_f32_e32 v80, v184, v80
	v_mul_f32_e32 v81, v185, v81
	v_mul_f32_e32 v82, v186, v82
	v_mul_f32_e32 v83, v187, v83
	v_mul_f32_e32 v84, v188, v84
	v_mul_f32_e32 v85, v189, v85
	v_mul_f32_e32 v86, v190, v86
	v_mul_f32_e32 v87, v191, v87
	v_mul_f32_e32 v246, v215, v84
	v_mul_f32_e32 v247, v214, v84
	v_fma_f32 v84, v215, v80, v247
	v_fma_f32 v80, v214, v80, -v246
	v_mul_f32_e32 v246, v217, v85
	v_mul_f32_e32 v247, v216, v85
	v_fma_f32 v85, v217, v81, v247
	v_fma_f32 v81, v216, v81, -v246
	v_mul_f32_e32 v246, v219, v86
	v_mul_f32_e32 v247, v218, v86
	v_fma_f32 v86, v219, v82, v247
	v_fma_f32 v82, v218, v82, -v246
	v_mul_f32_e32 v246, v221, v87
	v_mul_f32_e32 v247, v220, v87
	v_fma_f32 v87, v221, v83, v247
	v_fma_f32 v83, v220, v83, -v246
	v_cvt_pk_bf16_f32 v32, v80, v81
	v_cvt_pk_bf16_f32 v33, v82, v83
	v_cvt_pk_bf16_f32 v34, v84, v85
	v_cvt_pk_bf16_f32 v35, v86, v87
	s_nop 1
	v_permlane16_swap_b32_e32 v32, v34
	v_permlane16_swap_b32_e32 v33, v35
	global_store_dwordx4 v[248:249], v[32:35], off
	s_waitcnt lgkmcnt(0)
	ds_read_b128 v[214:217], v199
	ds_read_b128 v[218:221], v199 offset:16
	v_add_f32_e32 v246, v244, v228
	v_fma_f32 v246, v246, s26, v230
	v_rsq_f32_e32 v246, v246
	v_lshl_add_u64 v[248:249], vcc, 0, v[208:209]
	v_mul_f32_e32 v72, v72, v246
	v_mul_f32_e32 v73, v73, v246
	v_mul_f32_e32 v74, v74, v246
	v_mul_f32_e32 v75, v75, v246
	v_mul_f32_e32 v76, v76, v246
	v_mul_f32_e32 v77, v77, v246
	v_mul_f32_e32 v78, v78, v246
	v_mul_f32_e32 v79, v79, v246
	v_mul_f32_e32 v72, v184, v72
	v_mul_f32_e32 v73, v185, v73
	v_mul_f32_e32 v74, v186, v74
	v_mul_f32_e32 v75, v187, v75
	v_mul_f32_e32 v76, v188, v76
	v_mul_f32_e32 v77, v189, v77
	v_mul_f32_e32 v78, v190, v78
	v_mul_f32_e32 v79, v191, v79
	v_mul_f32_e32 v246, v201, v76
	v_mul_f32_e32 v247, v200, v76
	v_fma_f32 v76, v201, v72, v247
	v_fma_f32 v72, v200, v72, -v246
	v_mul_f32_e32 v246, v203, v77
	v_mul_f32_e32 v247, v202, v77
	v_fma_f32 v77, v203, v73, v247
	v_fma_f32 v73, v202, v73, -v246
	v_mul_f32_e32 v246, v205, v78
	v_mul_f32_e32 v247, v204, v78
	v_fma_f32 v78, v205, v74, v247
	v_fma_f32 v74, v204, v74, -v246
	v_mul_f32_e32 v246, v207, v79
	v_mul_f32_e32 v247, v206, v79
	v_fma_f32 v79, v207, v75, v247
	v_fma_f32 v75, v206, v75, -v246
	v_cvt_pk_bf16_f32 v232, v72, v73
	v_cvt_pk_bf16_f32 v233, v74, v75
	v_cvt_pk_bf16_f32 v234, v76, v77
	v_cvt_pk_bf16_f32 v235, v78, v79
	s_nop 1
	v_permlane16_swap_b32_e32 v232, v234
	v_permlane16_swap_b32_e32 v233, v235
	global_store_dwordx4 v[208:209], v[232:235], off
	s_waitcnt lgkmcnt(0)
	v_add_f32_e32 v246, v245, v229
	v_fma_f32 v246, v246, s26, v230
	v_rsq_f32_e32 v246, v246
	s_nop 0
	v_mul_f32_e32 v64, v64, v246
	v_mul_f32_e32 v65, v65, v246
	v_mul_f32_e32 v66, v66, v246
	v_mul_f32_e32 v67, v67, v246
	v_mul_f32_e32 v68, v68, v246
	v_mul_f32_e32 v69, v69, v246
	v_mul_f32_e32 v70, v70, v246
	v_mul_f32_e32 v71, v71, v246
	v_mul_f32_e32 v64, v184, v64
	v_mul_f32_e32 v65, v185, v65
	v_mul_f32_e32 v66, v186, v66
	v_mul_f32_e32 v67, v187, v67
	v_mul_f32_e32 v68, v188, v68
	v_mul_f32_e32 v69, v189, v69
	v_mul_f32_e32 v70, v190, v70
	v_mul_f32_e32 v71, v191, v71
	v_mul_f32_e32 v246, v215, v68
	v_mul_f32_e32 v247, v214, v68
	v_fma_f32 v68, v215, v64, v247
	v_fma_f32 v64, v214, v64, -v246
	v_mul_f32_e32 v246, v217, v69
	v_mul_f32_e32 v247, v216, v69
	v_fma_f32 v69, v217, v65, v247
	v_fma_f32 v65, v216, v65, -v246
	v_mul_f32_e32 v246, v219, v70
	v_mul_f32_e32 v247, v218, v70
	v_fma_f32 v70, v219, v66, v247
	v_fma_f32 v66, v218, v66, -v246
	v_mul_f32_e32 v246, v221, v71
	v_mul_f32_e32 v247, v220, v71
	v_fma_f32 v71, v221, v67, v247
	v_fma_f32 v67, v220, v67, -v246
	v_cvt_pk_bf16_f32 v32, v64, v65
	v_cvt_pk_bf16_f32 v33, v66, v67
	v_cvt_pk_bf16_f32 v34, v68, v69
	v_cvt_pk_bf16_f32 v35, v70, v71
	s_nop 1
	v_permlane16_swap_b32_e32 v32, v34
	v_permlane16_swap_b32_e32 v33, v35
	global_store_dwordx4 v[248:249], v[32:35], off

.Lq1_rows:
	ds_read_b128 v[200:203], v192
	ds_read_b128 v[204:207], v192 offset:16
	v_mul_u32_u24_e32 v246, s33, v146
	v_add3_u32 v246, v246, v138, v136
	s_lshl_b32 s0, s10, 1
	v_add_u32_e32 v246, s0, v246
	v_mov_b32_e32 v209, s93
	v_add_co_u32_e32 v208, vcc, s92, v246
	s_nop 1
	v_addc_co_u32_e32 v209, vcc, 0, v209, vcc
	s_mov_b32 vcc_lo, 0x12000
	s_mov_b32 vcc_hi, 0
	s_mov_b32 s26, 0x3c800000
	s_waitcnt lgkmcnt(0)
	v_mul_f32_e32 v184, s28, v184
	v_mul_f32_e32 v185, s28, v185
	v_mul_f32_e32 v186, s28, v186
	v_mul_f32_e32 v187, s28, v187
	v_mul_f32_e32 v188, s28, v188
	v_mul_f32_e32 v189, s28, v189
	v_mul_f32_e32 v190, s28, v190
	v_mul_f32_e32 v191, s28, v191
	ds_read_b128 v[214:217], v193
	ds_read_b128 v[218:221], v193 offset:16
	v_add_f32_e32 v246, v238, v222
	v_fma_f32 v246, v246, s26, v230
	v_rsq_f32_e32 v246, v246
	v_lshl_add_u64 v[248:249], vcc, 0, v[208:209]
	v_mul_f32_e32 v56, v56, v246
	v_mul_f32_e32 v57, v57, v246
	v_mul_f32_e32 v58, v58, v246
	v_mul_f32_e32 v59, v59, v246
	v_mul_f32_e32 v60, v60, v246
	v_mul_f32_e32 v61, v61, v246
	v_mul_f32_e32 v62, v62, v246
	v_mul_f32_e32 v63, v63, v246
	v_mul_f32_e32 v56, v184, v56
	v_mul_f32_e32 v57, v185, v57
	v_mul_f32_e32 v58, v186, v58
	v_mul_f32_e32 v59, v187, v59
	v_mul_f32_e32 v60, v188, v60
	v_mul_f32_e32 v61, v189, v61
	v_mul_f32_e32 v62, v190, v62
	v_mul_f32_e32 v63, v191, v63
	v_mul_f32_e32 v246, v201, v60
	v_mul_f32_e32 v247, v200, v60
	v_fma_f32 v60, v201, v56, v247
	v_fma_f32 v56, v200, v56, -v246
	v_mul_f32_e32 v246, v203, v61
	v_mul_f32_e32 v247, v202, v61
	v_fma_f32 v61, v203, v57, v247
	v_fma_f32 v57, v202, v57, -v246
	v_mul_f32_e32 v246, v205, v62
	v_mul_f32_e32 v247, v204, v62
	v_fma_f32 v62, v205, v58, v247
	v_fma_f32 v58, v204, v58, -v246
	v_mul_f32_e32 v246, v207, v63
	v_mul_f32_e32 v247, v206, v63
	v_fma_f32 v63, v207, v59, v247
	v_fma_f32 v59, v206, v59, -v246
	v_cvt_pk_bf16_f32 v232, v56, v57
	v_cvt_pk_bf16_f32 v233, v58, v59
	v_cvt_pk_bf16_f32 v234, v60, v61
	v_cvt_pk_bf16_f32 v235, v62, v63
	s_nop 1
	v_permlane16_swap_b32_e32 v232, v234
	v_permlane16_swap_b32_e32 v233, v235
	global_store_dwordx4 v[208:209], v[232:235], off offset:256
	s_waitcnt lgkmcnt(0)
	ds_read_b128 v[200:203], v194
	ds_read_b128 v[204:207], v194 offset:16
	v_add_f32_e32 v246, v239, v223
	v_fma_f32 v246, v246, s26, v230
	v_rsq_f32_e32 v246, v246
	v_lshl_add_u64 v[208:209], vcc, 0, v[248:249]
	v_mul_f32_e32 v48, v48, v246
	v_mul_f32_e32 v49, v49, v246
	v_mul_f32_e32 v50, v50, v246
	v_mul_f32_e32 v51, v51, v246
	v_mul_f32_e32 v52, v52, v246
	v_mul_f32_e32 v53, v53, v246
	v_mul_f32_e32 v54, v54, v246
	v_mul_f32_e32 v55, v55, v246
	v_mul_f32_e32 v48, v184, v48
	v_mul_f32_e32 v49, v185, v49
	v_mul_f32_e32 v50, v186, v50
	v_mul_f32_e32 v51, v187, v51
	v_mul_f32_e32 v52, v188, v52
	v_mul_f32_e32 v53, v189, v53
	v_mul_f32_e32 v54, v190, v54
	v_mul_f32_e32 v55, v191, v55
	v_mul_f32_e32 v246, v215, v52
	v_mul_f32_e32 v247, v214, v52
	v_fma_f32 v52, v215, v48, v247
	v_fma_f32 v48, v214, v48, -v246
	v_mul_f32_e32 v246, v217, v53
	v_mul_f32_e32 v247, v216, v53
	v_fma_f32 v53, v217, v49, v247
	v_fma_f32 v49, v216, v49, -v246
	v_mul_f32_e32 v246, v219, v54
	v_mul_f32_e32 v247, v218, v54
	v_fma_f32 v54, v219, v50, v247
	v_fma_f32 v50, v218, v50, -v246
	v_mul_f32_e32 v246, v221, v55
	v_mul_f32_e32 v247, v220, v55
	v_fma_f32 v55, v221, v51, v247
	v_fma_f32 v51, v220, v51, -v246
	v_cvt_pk_bf16_f32 v32, v48, v49
	v_cvt_pk_bf16_f32 v33, v50, v51
	v_cvt_pk_bf16_f32 v34, v52, v53
	v_cvt_pk_bf16_f32 v35, v54, v55
	s_nop 1
	v_permlane16_swap_b32_e32 v32, v34
	v_permlane16_swap_b32_e32 v33, v35
	global_store_dwordx4 v[248:249], v[32:35], off offset:256
	s_waitcnt lgkmcnt(0)
	ds_read_b128 v[214:217], v195
	ds_read_b128 v[218:221], v195 offset:16
	v_add_f32_e32 v246, v240, v224
	v_fma_f32 v246, v246, s26, v230
	v_rsq_f32_e32 v246, v246
	v_lshl_add_u64 v[248:249], vcc, 0, v[208:209]
	v_mul_f32_e32 v40, v40, v246
	v_mul_f32_e32 v41, v41, v246
	v_mul_f32_e32 v42, v42, v246
	v_mul_f32_e32 v43, v43, v246
	v_mul_f32_e32 v44, v44, v246
	v_mul_f32_e32 v45, v45, v246
	v_mul_f32_e32 v46, v46, v246
	v_mul_f32_e32 v47, v47, v246
	v_mul_f32_e32 v40, v184, v40
	v_mul_f32_e32 v41, v185, v41
	v_mul_f32_e32 v42, v186, v42
	v_mul_f32_e32 v43, v187, v43
	v_mul_f32_e32 v44, v188, v44
	v_mul_f32_e32 v45, v189, v45
	v_mul_f32_e32 v46, v190, v46
	v_mul_f32_e32 v47, v191, v47
	v_mul_f32_e32 v246, v201, v44
	v_mul_f32_e32 v247, v200, v44
	v_fma_f32 v44, v201, v40, v247
	v_fma_f32 v40, v200, v40, -v246
	v_mul_f32_e32 v246, v203, v45
	v_mul_f32_e32 v247, v202, v45
	v_fma_f32 v45, v203, v41, v247
	v_fma_f32 v41, v202, v41, -v246
	v_mul_f32_e32 v246, v205, v46
	v_mul_f32_e32 v247, v204, v46
	v_fma_f32 v46, v205, v42, v247
	v_fma_f32 v42, v204, v42, -v246
	v_mul_f32_e32 v246, v207, v47
	v_mul_f32_e32 v247, v206, v47
	v_fma_f32 v47, v207, v43, v247
	v_fma_f32 v43, v206, v43, -v246
	v_cvt_pk_bf16_f32 v232, v40, v41
	v_cvt_pk_bf16_f32 v233, v42, v43
	v_cvt_pk_bf16_f32 v234, v44, v45
	v_cvt_pk_bf16_f32 v235, v46, v47
	s_nop 1
	v_permlane16_swap_b32_e32 v232, v234
	v_permlane16_swap_b32_e32 v233, v235
	global_store_dwordx4 v[208:209], v[232:235], off offset:256
	s_waitcnt lgkmcnt(0)
	ds_read_b128 v[200:203], v196
	ds_read_b128 v[204:207], v196 offset:16
	v_add_f32_e32 v246, v241, v225
	v_fma_f32 v246, v246, s26, v230
	v_rsq_f32_e32 v246, v246
	s_mov_b32 vcc_lo, 0x5a000
	v_lshl_add_u64 v[208:209], vcc, 0, v[248:249]
	s_mov_b32 vcc_lo, 0x12000
	v_mul_f32_e32 v180, v180, v246
	v_mul_f32_e32 v181, v181, v246
	v_mul_f32_e32 v182, v182, v246
	v_mul_f32_e32 v183, v183, v246
	v_mul_f32_e32 v36, v36, v246
	v_mul_f32_e32 v37, v37, v246
	v_mul_f32_e32 v38, v38, v246
	v_mul_f32_e32 v39, v39, v246
	v_mul_f32_e32 v180, v184, v180
	v_mul_f32_e32 v181, v185, v181
	v_mul_f32_e32 v182, v186, v182
	v_mul_f32_e32 v183, v187, v183
	v_mul_f32_e32 v36, v188, v36
	v_mul_f32_e32 v37, v189, v37
	v_mul_f32_e32 v38, v190, v38
	v_mul_f32_e32 v39, v191, v39
	v_mul_f32_e32 v246, v215, v36
	v_mul_f32_e32 v247, v214, v36
	v_fma_f32 v36, v215, v180, v247
	v_fma_f32 v180, v214, v180, -v246
	v_mul_f32_e32 v246, v217, v37
	v_mul_f32_e32 v247, v216, v37
	v_fma_f32 v37, v217, v181, v247
	v_fma_f32 v181, v216, v181, -v246
	v_mul_f32_e32 v246, v219, v38
	v_mul_f32_e32 v247, v218, v38
	v_fma_f32 v38, v219, v182, v247
	v_fma_f32 v182, v218, v182, -v246
	v_mul_f32_e32 v246, v221, v39
	v_mul_f32_e32 v247, v220, v39
	v_fma_f32 v39, v221, v183, v247
	v_fma_f32 v183, v220, v183, -v246
	v_cvt_pk_bf16_f32 v32, v180, v181
	v_cvt_pk_bf16_f32 v33, v182, v183
	v_cvt_pk_bf16_f32 v34, v36, v37
	v_cvt_pk_bf16_f32 v35, v38, v39
	s_nop 1
	v_permlane16_swap_b32_e32 v32, v34
	v_permlane16_swap_b32_e32 v33, v35
	global_store_dwordx4 v[248:249], v[32:35], off offset:256
	s_waitcnt lgkmcnt(0)
	ds_read_b128 v[214:217], v197
	ds_read_b128 v[218:221], v197 offset:16
	v_add_f32_e32 v246, v242, v226
	v_fma_f32 v246, v246, s26, v230
	v_rsq_f32_e32 v246, v246
	v_lshl_add_u64 v[248:249], vcc, 0, v[208:209]
	v_mul_f32_e32 v24, v24, v246
	v_mul_f32_e32 v25, v25, v246
	v_mul_f32_e32 v26, v26, v246
	v_mul_f32_e32 v27, v27, v246
	v_mul_f32_e32 v28, v28, v246
	v_mul_f32_e32 v29, v29, v246
	v_mul_f32_e32 v30, v30, v246
	v_mul_f32_e32 v31, v31, v246
	v_mul_f32_e32 v24, v184, v24
	v_mul_f32_e32 v25, v185, v25
	v_mul_f32_e32 v26, v186, v26
	v_mul_f32_e32 v27, v187, v27
	v_mul_f32_e32 v28, v188, v28
	v_mul_f32_e32 v29, v189, v29
	v_mul_f32_e32 v30, v190, v30
	v_mul_f32_e32 v31, v191, v31
	v_mul_f32_e32 v246, v201, v28
	v_mul_f32_e32 v247, v200, v28
	v_fma_f32 v28, v201, v24, v247
	v_fma_f32 v24, v200, v24, -v246
	v_mul_f32_e32 v246, v203, v29
	v_mul_f32_e32 v247, v202, v29
	v_fma_f32 v29, v203, v25, v247
	v_fma_f32 v25, v202, v25, -v246
	v_mul_f32_e32 v246, v205, v30
	v_mul_f32_e32 v247, v204, v30
	v_fma_f32 v30, v205, v26, v247
	v_fma_f32 v26, v204, v26, -v246
	v_mul_f32_e32 v246, v207, v31
	v_mul_f32_e32 v247, v206, v31
	v_fma_f32 v31, v207, v27, v247
	v_fma_f32 v27, v206, v27, -v246
	v_cvt_pk_bf16_f32 v232, v24, v25
	v_cvt_pk_bf16_f32 v233, v26, v27
	v_cvt_pk_bf16_f32 v234, v28, v29
	v_cvt_pk_bf16_f32 v235, v30, v31
	s_nop 1
	v_permlane16_swap_b32_e32 v232, v234
	v_permlane16_swap_b32_e32 v233, v235
	global_store_dwordx4 v[208:209], v[232:235], off offset:256
	s_waitcnt lgkmcnt(0)
	ds_read_b128 v[200:203], v198
	ds_read_b128 v[204:207], v198 offset:16
	v_add_f32_e32 v246, v243, v227
	v_fma_f32 v246, v246, s26, v230
	v_rsq_f32_e32 v246, v246
	v_lshl_add_u64 v[208:209], vcc, 0, v[248:249]
	v_mul_f32_e32 v16, v16, v246
	v_mul_f32_e32 v17, v17, v246
	v_mul_f32_e32 v18, v18, v246
	v_mul_f32_e32 v19, v19, v246
	v_mul_f32_e32 v20, v20, v246
	v_mul_f32_e32 v21, v21, v246
	v_mul_f32_e32 v22, v22, v246
	v_mul_f32_e32 v23, v23, v246
	v_mul_f32_e32 v16, v184, v16
	v_mul_f32_e32 v17, v185, v17
	v_mul_f32_e32 v18, v186, v18
	v_mul_f32_e32 v19, v187, v19
	v_mul_f32_e32 v20, v188, v20
	v_mul_f32_e32 v21, v189, v21
	v_mul_f32_e32 v22, v190, v22
	v_mul_f32_e32 v23, v191, v23
	v_mul_f32_e32 v246, v215, v20
	v_mul_f32_e32 v247, v214, v20
	v_fma_f32 v20, v215, v16, v247
	v_fma_f32 v16, v214, v16, -v246
	v_mul_f32_e32 v246, v217, v21
	v_mul_f32_e32 v247, v216, v21
	v_fma_f32 v21, v217, v17, v247
	v_fma_f32 v17, v216, v17, -v246
	v_mul_f32_e32 v246, v219, v22
	v_mul_f32_e32 v247, v218, v22
	v_fma_f32 v22, v219, v18, v247
	v_fma_f32 v18, v218, v18, -v246
	v_mul_f32_e32 v246, v221, v23
	v_mul_f32_e32 v247, v220, v23
	v_fma_f32 v23, v221, v19, v247
	v_fma_f32 v19, v220, v19, -v246
	v_cvt_pk_bf16_f32 v32, v16, v17
	v_cvt_pk_bf16_f32 v33, v18, v19
	v_cvt_pk_bf16_f32 v34, v20, v21
	v_cvt_pk_bf16_f32 v35, v22, v23
	s_nop 1
	v_permlane16_swap_b32_e32 v32, v34
	v_permlane16_swap_b32_e32 v33, v35
	global_store_dwordx4 v[248:249], v[32:35], off offset:256
	s_waitcnt lgkmcnt(0)
	ds_read_b128 v[214:217], v199
	ds_read_b128 v[218:221], v199 offset:16
	v_add_f32_e32 v246, v244, v228
	v_fma_f32 v246, v246, s26, v230
	v_rsq_f32_e32 v246, v246
	v_lshl_add_u64 v[248:249], vcc, 0, v[208:209]
	v_mul_f32_e32 v8, v8, v246
	v_mul_f32_e32 v9, v9, v246
	v_mul_f32_e32 v10, v10, v246
	v_mul_f32_e32 v11, v11, v246
	v_mul_f32_e32 v12, v12, v246
	v_mul_f32_e32 v13, v13, v246
	v_mul_f32_e32 v14, v14, v246
	v_mul_f32_e32 v15, v15, v246
	v_mul_f32_e32 v8, v184, v8
	v_mul_f32_e32 v9, v185, v9
	v_mul_f32_e32 v10, v186, v10
	v_mul_f32_e32 v11, v187, v11
	v_mul_f32_e32 v12, v188, v12
	v_mul_f32_e32 v13, v189, v13
	v_mul_f32_e32 v14, v190, v14
	v_mul_f32_e32 v15, v191, v15
	v_mul_f32_e32 v246, v201, v12
	v_mul_f32_e32 v247, v200, v12
	v_fma_f32 v12, v201, v8, v247
	v_fma_f32 v8, v200, v8, -v246
	v_mul_f32_e32 v246, v203, v13
	v_mul_f32_e32 v247, v202, v13
	v_fma_f32 v13, v203, v9, v247
	v_fma_f32 v9, v202, v9, -v246
	v_mul_f32_e32 v246, v205, v14
	v_mul_f32_e32 v247, v204, v14
	v_fma_f32 v14, v205, v10, v247
	v_fma_f32 v10, v204, v10, -v246
	v_mul_f32_e32 v246, v207, v15
	v_mul_f32_e32 v247, v206, v15
	v_fma_f32 v15, v207, v11, v247
	v_fma_f32 v11, v206, v11, -v246
	v_cvt_pk_bf16_f32 v232, v8, v9
	v_cvt_pk_bf16_f32 v233, v10, v11
	v_cvt_pk_bf16_f32 v234, v12, v13
	v_cvt_pk_bf16_f32 v235, v14, v15
	s_nop 1
	v_permlane16_swap_b32_e32 v232, v234
	v_permlane16_swap_b32_e32 v233, v235
	global_store_dwordx4 v[208:209], v[232:235], off offset:256
	s_waitcnt lgkmcnt(0)
	v_add_f32_e32 v246, v245, v229
	v_fma_f32 v246, v246, s26, v230
	v_rsq_f32_e32 v246, v246
	s_nop 0
	v_mul_f32_e32 v0, v0, v246
	v_mul_f32_e32 v1, v1, v246
	v_mul_f32_e32 v2, v2, v246
	v_mul_f32_e32 v3, v3, v246
	v_mul_f32_e32 v4, v4, v246
	v_mul_f32_e32 v5, v5, v246
	v_mul_f32_e32 v6, v6, v246
	v_mul_f32_e32 v7, v7, v246
	v_mul_f32_e32 v0, v184, v0
	v_mul_f32_e32 v1, v185, v1
	v_mul_f32_e32 v2, v186, v2
	v_mul_f32_e32 v3, v187, v3
	v_mul_f32_e32 v4, v188, v4
	v_mul_f32_e32 v5, v189, v5
	v_mul_f32_e32 v6, v190, v6
	v_mul_f32_e32 v7, v191, v7
	v_mul_f32_e32 v246, v215, v4
	v_mul_f32_e32 v247, v214, v4
	v_fma_f32 v4, v215, v0, v247
	v_fma_f32 v0, v214, v0, -v246
	v_mul_f32_e32 v246, v217, v5
	v_mul_f32_e32 v247, v216, v5
	v_fma_f32 v5, v217, v1, v247
	v_fma_f32 v1, v216, v1, -v246
	v_mul_f32_e32 v246, v219, v6
	v_mul_f32_e32 v247, v218, v6
	v_fma_f32 v6, v219, v2, v247
	v_fma_f32 v2, v218, v2, -v246
	v_mul_f32_e32 v246, v221, v7
	v_mul_f32_e32 v247, v220, v7
	v_fma_f32 v7, v221, v3, v247
	v_fma_f32 v3, v220, v3, -v246
	v_cvt_pk_bf16_f32 v32, v0, v1
	v_cvt_pk_bf16_f32 v33, v2, v3
	v_cvt_pk_bf16_f32 v34, v4, v5
	v_cvt_pk_bf16_f32 v35, v6, v7
	s_nop 1
	v_permlane16_swap_b32_e32 v32, v34
	v_permlane16_swap_b32_e32 v33, v35
	global_store_dwordx4 v[248:249], v[32:35], off offset:256
	s_branch .LBB0_74
